# gla chain loader lightly paced (4 x s_sleep 1 per step, inside its ~5 us slack) to leave memory bandwidth to the critical gdn chains
# speedup vs baseline: 1.0068x; 1.0068x over previous
; #define LBAR() do { asm volatile("s_waitcnt lgkmcnt(0)" ::: "memory"); __builtin_amdgcn_s_barrier(); asm volatile("" ::: "memory"); } while (0)
; #define WAITV(N_) asm volatile("s_waitcnt vmcnt(" #N_ ")" ::: "memory")
; #define ISSUE_XG(s_) do { const unsigned char* g_ = A.blob + (unit0 + CHUNK_OF(s_)) * BLOB + lane * 16; const unsigned l_ = lds0 + ((s_) & 1) * C_BUF; \
;         _Pragma("unroll") for (int k = 0; k < 8; ++k) { const unsigned o_ = (lw + 4 * k) * 1024; DMA1(g_ + o_, l_ + o_); __builtin_amdgcn_s_sleep(LOADER_PACE); } } while (0)
; #define WAITV(N_) asm volatile("s_waitcnt vmcnt(" #N_ ")" ::: "memory")
; #define ISSUE_XG(s_) do { const unsigned char* g_ = A.blobA + (unit0 + CHUNK_OF(s_)) * BLOBA + qo + lane * 16; const unsigned l_ = lds0 + ((s_) & 1) * CB_BUF; \
;         _Pragma("unroll") for (int k = 0; k < 4; ++k) { const unsigned o_ = (lw + 4 * k) * 1024; DMA1(g_ + o_, l_ + o_); } } while (0)
; __device__ __forceinline__ void gla_chain_unit(LAS unsigned char* lds, const GlaChainArgs& A, int item, int half) {
;     ...
;         if (!(flags & 4)) { ISSUE_XG(0); ISSUE_YG(0); ISSUE_XG(1); }
;         WAITV(0);
;         LBAR();
;         for (int s = 0; s < NCH; ++s) {
;             if (s + 1 < NCH && !(flags & 4)) ISSUE_YG(s + 1);
.LBB0_623:
	s_add_i32 s44, s45, 1
	s_and_b64 s[2:3], s[52:53], exec
	s_cselect_b32 s2, s44, s43
	s_add_i32 s34, s2, s60
	v_mad_u64_u32 v[8:9], s[2:3], s34, v171, v[2:3]
	s_lshl_b64 s[2:3], s[34:35], 16
	s_bitcmp1_b32 s44, 0
	v_readlane_b32 s46, v252, 48
	s_cselect_b32 s34, s42, 0
	v_readlane_b32 s47, v252, 49
	v_lshl_add_u64 v[10:11], v[4:5], 0, s[2:3]
	s_add_i32 s3, s34, 0x4400
	v_lshl_add_u64 v[12:13], v[8:9], 0, s[46:47]
	v_lshl_add_u64 v[14:15], v[12:13], 0, s[4:5]
	s_add_i32 s46, s3, s4
	s_mov_b32 m0, s46
	s_nop 0
	global_load_lds_dwordx4 v[14:15], off
	v_lshl_add_u64 v[14:15], v[12:13], 0, s[6:7]
	s_add_i32 s46, s3, s6
	s_mov_b32 m0, s46
	s_nop 0
	global_load_lds_dwordx4 v[14:15], off
	s_sleep 1
	v_lshl_add_u64 v[14:15], v[12:13], 0, s[36:37]
	s_add_i32 s46, s3, s36
	s_mov_b32 m0, s46
	s_nop 0
	global_load_lds_dwordx4 v[14:15], off
	s_add_i32 s2, s34, 0x8400
	v_lshl_add_u64 v[12:13], v[12:13], 0, s[38:39]
	s_add_i32 s3, s3, s38
	s_mov_b32 m0, s3
	s_nop 0
	global_load_lds_dwordx4 v[12:13], off
	s_sleep 1
	v_lshl_add_u64 v[12:13], v[10:11], 0, s[4:5]
	s_add_i32 s3, s2, s4
	s_mov_b32 m0, s3
	s_nop 0
	global_load_lds_dwordx4 v[12:13], off
	v_lshl_add_u64 v[12:13], v[10:11], 0, s[6:7]
	s_add_i32 s3, s2, s6
	s_mov_b32 m0, s3
	s_nop 0
	global_load_lds_dwordx4 v[12:13], off
	s_sleep 1
	v_lshl_add_u64 v[12:13], v[10:11], 0, s[36:37]
	s_add_i32 s3, s2, s36
	s_mov_b32 m0, s3
	s_nop 0
	global_load_lds_dwordx4 v[12:13], off
	v_lshl_add_u64 v[10:11], v[10:11], 0, s[38:39]
	s_add_i32 s46, s2, s38
	s_mov_b32 m0, s46
	s_nop 0
	global_load_lds_dwordx4 v[10:11], off
	s_sleep 1
	v_cndmask_b32_e64 v12, 0, 1, s[40:41]
	v_cmp_ne_u32_e64 s[2:3], 1, v12
	s_andn2_b64 vcc, exec, s[40:41]
	s_cbranch_vccnz .LBB0_622
	s_mov_b64 s[46:47], 0x8000
	v_lshl_add_u64 v[8:9], v[8:9], 0, s[46:47]
	s_addk_i32 s34, 0x4000
	s_mov_b32 m0, s34
	s_nop 0
	global_load_lds_dwordx4 v[8:9], off
	s_branch .LBB0_622
